# attention QK: K fragments read in consumption order with per-MFMA lgkmcnt waits, V reads in the MFMA gaps; rescale decision chain shortened to one compare+branch
# baseline (speedup 1.0000x reference)
.LBB0_514:
	s_cmp_gt_i32 s23, s86
	s_cbranch_scc1 .LBB0_510
	s_mul_i32 s13, s27, 0x6000
	s_add_i32 s13, s13, 0
	s_cmpk_gt_i32 s25, 0x70
	s_cselect_b64 vcc, -1, 0
	s_add_i32 s28, s13, 0x2000
	v_add_u32_e32 v156, s28, v205
	v_add_u32_e32 v0, s13, v205
	v_add_u32_e32 v82, s13, v206
	v_add_u32_e32 v83, s13, v207
	v_add_u32_e32 v84, s13, v208
	ds_read_b128 v[174:177], v0
	ds_read_b128 v[190:193], v0 offset:4096
	ds_read_b128 v[178:181], v82
	ds_read_b128 v[194:197], v82 offset:4096
	ds_read_b128 v[182:185], v83
	ds_read_b128 v[198:201], v83 offset:4096
	ds_read_b128 v[186:189], v84
	ds_read_b128 v[220:223], v84 offset:4096
	s_waitcnt lgkmcnt(8)
	v_cndmask_b32_e32 v157, 0, v238, vcc
	v_xor_b32_e32 v0, 32, v156
	v_sub_f32_e32 v66, v157, v154
	v_mov_b32_e32 v67, v66
	v_mov_b32_e32 v68, v66
	v_mov_b32_e32 v69, v66
	v_mov_b32_e32 v70, v66
	v_mov_b32_e32 v71, v66
	v_mov_b32_e32 v72, v66
	v_mov_b32_e32 v73, v66
	v_mov_b32_e32 v74, v66
	v_mov_b32_e32 v75, v66
	v_mov_b32_e32 v76, v66
	v_mov_b32_e32 v77, v66
	v_mov_b32_e32 v78, v66
	v_mov_b32_e32 v79, v66
	v_mov_b32_e32 v80, v66
	v_mov_b32_e32 v81, v66
	s_and_b64 vcc, exec, vcc
	s_nop 0
	s_waitcnt lgkmcnt(7)
	v_mfma_f32_32x32x16_bf16 v[82:97], v[174:177], v[230:233], v[66:81]
	s_waitcnt lgkmcnt(6)
	v_mfma_f32_32x32x16_bf16 v[66:81], v[190:193], v[230:233], v[66:81]
	ds_read_b128 v[126:129], v156
	ds_read_b128 v[122:125], v156 offset:4096
	s_waitcnt lgkmcnt(7)
	v_mfma_f32_32x32x16_bf16 v[82:97], v[178:181], v[234:237], v[82:97]
	s_waitcnt lgkmcnt(6)
	v_mfma_f32_32x32x16_bf16 v[66:81], v[194:197], v[234:237], v[66:81]
	ds_read_b128 v[118:121], v156 offset:8192
	ds_read_b128 v[114:117], v156 offset:12288
	s_waitcnt lgkmcnt(7)
	v_mfma_f32_32x32x16_bf16 v[82:97], v[182:185], v[242:245], v[82:97]
	s_waitcnt lgkmcnt(6)
	v_mfma_f32_32x32x16_bf16 v[66:81], v[198:201], v[242:245], v[66:81]
	ds_read_b128 v[110:113], v0
	ds_read_b128 v[106:109], v0 offset:4096
	s_waitcnt lgkmcnt(7)
	v_mfma_f32_32x32x16_bf16 v[82:97], v[186:189], v[246:249], v[82:97]
	s_waitcnt lgkmcnt(6)
	v_mfma_f32_32x32x16_bf16 v[66:81], v[220:223], v[246:249], v[66:81]
	ds_read_b128 v[102:105], v0 offset:8192
	ds_read_b128 v[98:101], v0 offset:12288
	s_cbranch_vccnz .LBB0_517
	v_add_u32_e32 v0, s26, v214
	v_add_u32_e32 v157, 0x18094, v0
	ds_read2_b32 v[158:159], v157 offset0:58 offset1:59
	ds_read2_b32 v[160:161], v157 offset0:26 offset1:27
	ds_read2_b32 v[162:163], v157 offset0:56 offset1:57
	ds_read2_b32 v[164:165], v157 offset0:24 offset1:25
	ds_read2_b32 v[166:167], v157 offset0:50 offset1:51
	ds_read2_b32 v[168:169], v157 offset0:18 offset1:19
	ds_read2_b32 v[174:175], v157 offset0:48 offset1:49
	ds_read2_b32 v[176:177], v157 offset0:16 offset1:17
	ds_read2_b32 v[178:179], v157 offset0:42 offset1:43
	ds_read2_b32 v[180:181], v157 offset0:10 offset1:11
	ds_read2_b32 v[182:183], v157 offset0:40 offset1:41
	ds_read2_b32 v[184:185], v157 offset0:8 offset1:9
	ds_read2_b32 v[190:191], v157 offset0:34 offset1:35
	ds_read2_b32 v[192:193], v157 offset0:2 offset1:3
	ds_read2_b32 v[194:195], v157 offset0:32 offset1:33
	ds_read2_b32 v[196:197], v157 offset0:0 offset1:1
	s_waitcnt lgkmcnt(0)
	v_pk_add_f32 v[82:83], v[82:83], v[158:159] op_sel:[0,1] op_sel_hi:[1,0]
	v_pk_add_f32 v[66:67], v[66:67], v[160:161] op_sel:[0,1] op_sel_hi:[1,0]
	v_pk_add_f32 v[84:85], v[84:85], v[162:163] op_sel:[0,1] op_sel_hi:[1,0]
	v_pk_add_f32 v[68:69], v[68:69], v[164:165] op_sel:[0,1] op_sel_hi:[1,0]
	v_pk_add_f32 v[86:87], v[86:87], v[166:167] op_sel:[0,1] op_sel_hi:[1,0]
	v_pk_add_f32 v[70:71], v[70:71], v[168:169] op_sel:[0,1] op_sel_hi:[1,0]
	v_pk_add_f32 v[88:89], v[88:89], v[174:175] op_sel:[0,1] op_sel_hi:[1,0]
	v_pk_add_f32 v[72:73], v[72:73], v[176:177] op_sel:[0,1] op_sel_hi:[1,0]
	v_pk_add_f32 v[90:91], v[90:91], v[178:179] op_sel:[0,1] op_sel_hi:[1,0]
	v_pk_add_f32 v[74:75], v[74:75], v[180:181] op_sel:[0,1] op_sel_hi:[1,0]
	v_pk_add_f32 v[92:93], v[92:93], v[182:183] op_sel:[0,1] op_sel_hi:[1,0]
	v_pk_add_f32 v[76:77], v[76:77], v[184:185] op_sel:[0,1] op_sel_hi:[1,0]
	v_pk_add_f32 v[94:95], v[94:95], v[190:191] op_sel:[0,1] op_sel_hi:[1,0]
	v_pk_add_f32 v[78:79], v[78:79], v[192:193] op_sel:[0,1] op_sel_hi:[1,0]
	v_pk_add_f32 v[96:97], v[96:97], v[194:195] op_sel:[0,1] op_sel_hi:[1,0]
	v_pk_add_f32 v[80:81], v[80:81], v[196:197] op_sel:[0,1] op_sel_hi:[1,0]
.LBB0_517:
	s_nop 10
	v_max3_f32 v0, v82, v66, v83
	v_max3_f32 v157, v67, v84, v68
	v_max3_f32 v0, v0, v85, v69
	v_max3_f32 v157, v157, v86, v70
	v_max3_f32 v0, v0, v87, v71
	v_max3_f32 v157, v157, v88, v72
	v_max3_f32 v0, v0, v89, v73
	v_max3_f32 v157, v157, v90, v74
	v_max3_f32 v0, v0, v91, v75
	v_max3_f32 v157, v157, v92, v76
	v_max3_f32 v0, v0, v93, v77
	v_max3_f32 v157, v157, v94, v78
	v_max3_f32 v0, v0, v95, v79
	v_max3_f32 v157, v157, v96, v80
	v_max3_f32 v0, v0, v97, v81
	v_max_f32_e32 v0, v0, v157
	v_mov_b32_e32 v157, v0
	s_nop 1
	v_permlane32_swap_b32_e32 v0, v157
	s_cmp_eq_u32 s26, 0
	s_cselect_b64 s[44:45], -1, 0
	s_cmp_lg_u32 s26, 0
	v_max_f32_e32 v157, v0, v157
	s_cbranch_scc0 .Latt_first
	s_mov_b32 s13, 0x41000000
	v_cmp_lt_f32_e32 vcc, s13, v157
	s_cbranch_vccz .LBB0_509
	v_max_f32_e32 v0, v157, v157
	v_max_f32_e32 v0, 0, v0
	s_branch .Latt_rescale
.Latt_first:
	v_mov_b32_e32 v0, v157
.Latt_rescale:
	v_exp_f32_e64 v157, -v0
	v_add_f32_e32 v154, v154, v0
	v_pk_add_f32 v[82:83], v[82:83], v[0:1] op_sel_hi:[1,0] neg_lo:[0,1] neg_hi:[0,1]
	v_pk_add_f32 v[66:67], v[66:67], v[0:1] op_sel_hi:[1,0] neg_lo:[0,1] neg_hi:[0,1]
	v_cndmask_b32_e64 v158, v157, 1.0, s[44:45]
	v_pk_mul_f32 v[64:65], v[64:65], v[158:159] op_sel_hi:[1,0]
	v_pk_mul_f32 v[62:63], v[62:63], v[158:159] op_sel_hi:[1,0]
	v_pk_mul_f32 v[60:61], v[60:61], v[158:159] op_sel_hi:[1,0]
	v_pk_mul_f32 v[58:59], v[58:59], v[158:159] op_sel_hi:[1,0]
	v_pk_mul_f32 v[56:57], v[56:57], v[158:159] op_sel_hi:[1,0]
	v_pk_mul_f32 v[54:55], v[54:55], v[158:159] op_sel_hi:[1,0]
	v_pk_mul_f32 v[52:53], v[52:53], v[158:159] op_sel_hi:[1,0]
	v_pk_mul_f32 v[50:51], v[50:51], v[158:159] op_sel_hi:[1,0]
	v_pk_mul_f32 v[48:49], v[48:49], v[158:159] op_sel_hi:[1,0]
	v_pk_mul_f32 v[46:47], v[46:47], v[158:159] op_sel_hi:[1,0]
	v_pk_mul_f32 v[44:45], v[44:45], v[158:159] op_sel_hi:[1,0]
	v_pk_mul_f32 v[42:43], v[42:43], v[158:159] op_sel_hi:[1,0]
	v_pk_mul_f32 v[40:41], v[40:41], v[158:159] op_sel_hi:[1,0]
	v_pk_mul_f32 v[38:39], v[38:39], v[158:159] op_sel_hi:[1,0]
	v_pk_mul_f32 v[36:37], v[36:37], v[158:159] op_sel_hi:[1,0]
	v_pk_mul_f32 v[34:35], v[34:35], v[158:159] op_sel_hi:[1,0]
	v_pk_mul_f32 v[32:33], v[32:33], v[158:159] op_sel_hi:[1,0]
	v_pk_mul_f32 v[30:31], v[30:31], v[158:159] op_sel_hi:[1,0]
	v_pk_mul_f32 v[28:29], v[28:29], v[158:159] op_sel_hi:[1,0]
	v_pk_mul_f32 v[26:27], v[26:27], v[158:159] op_sel_hi:[1,0]
	v_pk_mul_f32 v[24:25], v[24:25], v[158:159] op_sel_hi:[1,0]
	v_pk_mul_f32 v[22:23], v[22:23], v[158:159] op_sel_hi:[1,0]
	v_pk_mul_f32 v[20:21], v[20:21], v[158:159] op_sel_hi:[1,0]
	v_pk_mul_f32 v[18:19], v[18:19], v[158:159] op_sel_hi:[1,0]
	v_pk_mul_f32 v[16:17], v[16:17], v[158:159] op_sel_hi:[1,0]
	v_pk_mul_f32 v[14:15], v[14:15], v[158:159] op_sel_hi:[1,0]
	v_pk_mul_f32 v[12:13], v[12:13], v[158:159] op_sel_hi:[1,0]
	v_pk_mul_f32 v[10:11], v[10:11], v[158:159] op_sel_hi:[1,0]
	v_pk_mul_f32 v[8:9], v[8:9], v[158:159] op_sel_hi:[1,0]
	v_pk_mul_f32 v[6:7], v[6:7], v[158:159] op_sel_hi:[1,0]
	v_pk_mul_f32 v[4:5], v[4:5], v[158:159] op_sel_hi:[1,0]
	v_pk_mul_f32 v[2:3], v[2:3], v[158:159] op_sel_hi:[1,0]
	v_pk_add_f32 v[84:85], v[84:85], v[0:1] op_sel_hi:[1,0] neg_lo:[0,1] neg_hi:[0,1]
	v_pk_add_f32 v[68:69], v[68:69], v[0:1] op_sel_hi:[1,0] neg_lo:[0,1] neg_hi:[0,1]
	v_pk_add_f32 v[86:87], v[86:87], v[0:1] op_sel_hi:[1,0] neg_lo:[0,1] neg_hi:[0,1]
	v_pk_add_f32 v[70:71], v[70:71], v[0:1] op_sel_hi:[1,0] neg_lo:[0,1] neg_hi:[0,1]
	v_pk_add_f32 v[88:89], v[88:89], v[0:1] op_sel_hi:[1,0] neg_lo:[0,1] neg_hi:[0,1]
	v_pk_add_f32 v[72:73], v[72:73], v[0:1] op_sel_hi:[1,0] neg_lo:[0,1] neg_hi:[0,1]
	v_pk_add_f32 v[90:91], v[90:91], v[0:1] op_sel_hi:[1,0] neg_lo:[0,1] neg_hi:[0,1]
	v_pk_add_f32 v[74:75], v[74:75], v[0:1] op_sel_hi:[1,0] neg_lo:[0,1] neg_hi:[0,1]
	v_pk_add_f32 v[92:93], v[92:93], v[0:1] op_sel_hi:[1,0] neg_lo:[0,1] neg_hi:[0,1]
	v_pk_add_f32 v[76:77], v[76:77], v[0:1] op_sel_hi:[1,0] neg_lo:[0,1] neg_hi:[0,1]
	v_pk_add_f32 v[94:95], v[94:95], v[0:1] op_sel_hi:[1,0] neg_lo:[0,1] neg_hi:[0,1]
	v_pk_add_f32 v[78:79], v[78:79], v[0:1] op_sel_hi:[1,0] neg_lo:[0,1] neg_hi:[0,1]
	v_pk_add_f32 v[96:97], v[96:97], v[0:1] op_sel_hi:[1,0] neg_lo:[0,1] neg_hi:[0,1]
	v_pk_add_f32 v[80:81], v[80:81], v[0:1] op_sel_hi:[1,0] neg_lo:[0,1] neg_hi:[0,1]
	v_mul_f32_e32 v155, v155, v158
	s_branch .LBB0_509
